# rwkv_post: all loads of an iteration issued at its top, ln_w/ln_b kept in registers
# speedup vs baseline: 1.0151x; 1.0081x over previous
.LBB0_894:
	v_readlane_b32 s70, v254, 5
	v_readlane_b32 s71, v254, 6
	s_mov_b64 s[12:13], s[70:71]
	v_mov_b32_e32 v0, v226
	v_readlane_b32 s0, v254, 0
	s_nop 1
	v_add_u32_e32 v40, s0, v0
	s_mov_b32 s0, 0x100000
	v_cmp_gt_i32_e32 vcc, s0, v40
	s_and_saveexec_b64 s[6:7], vcc
	v_readlane_b32 s38, v254, 1
	v_readlane_b32 s39, v254, 2
	s_mov_b64 s[90:91], 0x33f2900
	s_cbranch_execz .LBB0_901
	s_load_dwordx2 s[10:11], s[12:13], 0xc0
	s_load_dwordx4 s[20:23], s[12:13], 0x90
	v_and_b32_e32 v0, 7, v0
	v_lshlrev_b32_e32 v41, 3, v0
	s_waitcnt vmcnt(2)
	v_lshlrev_b32_e32 v16, 4, v0
	s_waitcnt lgkmcnt(0)
	s_add_u32 s12, s10, 0x33f0000
	s_addc_u32 s13, s11, 0
	s_add_u32 s14, s10, 0x15bf0000
	s_addc_u32 s15, s11, 0
	s_add_u32 s16, s10, 0x3370000
	s_addc_u32 s17, s11, 0
	s_lshl_b64 s[0:1], s[8:9], 2
	s_add_u32 s8, s20, s0
	s_addc_u32 s9, s21, s1
	s_add_u32 s18, s22, s0
	s_addc_u32 s19, s23, s1
	s_add_u32 s20, s10, 0x1ebfd000
	v_mov_b32_e32 v17, v145
	s_addc_u32 s21, s11, 0
	s_mov_b64 s[22:23], 0
	v_bfe_u32 v221, v40, 3, 3
	v_lshl_or_b32 v221, v221, 6, v41
	v_lshlrev_b32_e32 v221, 2, v221
	global_load_dwordx4 v[204:207], v221, s[8:9] offset:16
	global_load_dwordx4 v[200:203], v221, s[8:9]
	global_load_dwordx4 v[212:215], v221, s[18:19] offset:16
	global_load_dwordx4 v[208:211], v221, s[18:19]
	s_waitcnt vmcnt(0)
	s_branch .LBB0_897
.LBB0_896:
	s_or_b64 exec, exec, s[24:25]
	s_waitcnt vmcnt(3)
	v_add_f32_e32 v0, 0, v2
	v_add_f32_e32 v0, v3, v0
	v_add_f32_e32 v0, v4, v0
	v_add_f32_e32 v0, v5, v0
	s_waitcnt vmcnt(2)
	v_add_f32_e32 v0, v6, v0
	v_add_f32_e32 v0, v7, v0
	v_add_f32_e32 v0, v8, v0
	v_add_f32_e32 v0, v9, v0
	v_lshlrev_b32_e32 v144, 1, v31
	s_movk_i32 s0, 0x2000
	v_add_f32_dpp v0, v0, v0 quad_perm:[1,0,3,2] row_mask:0xf bank_mask:0xf bound_ctrl:1
	v_ashrrev_i32_e32 v19, 31, v18
	v_lshlrev_b64 v[50:51], 5, v[18:19]
	v_add_f32_dpp v0, v0, v0 quad_perm:[2,3,0,1] row_mask:0xf bank_mask:0xf bound_ctrl:1
	v_lshl_add_u64 v[50:51], s[16:17], 0, v[50:51]
	v_lshlrev_b32_e32 v30, 2, v30
	v_add_f32_dpp v0, v0, v0 row_half_mirror row_mask:0xf bank_mask:0xf bound_ctrl:1
	v_mul_f32_e32 v0, 0x3c800000, v0
	v_pk_add_f32 v[38:39], v[2:3], v[0:1] op_sel_hi:[1,0] neg_lo:[0,1] neg_hi:[0,1]
	v_pk_add_f32 v[32:33], v[4:5], v[0:1] op_sel_hi:[1,0] neg_lo:[0,1] neg_hi:[0,1]
	v_pk_mul_f32 v[2:3], v[38:39], v[38:39]
	v_pk_mul_f32 v[4:5], v[32:33], v[32:33]
	v_add_f32_e32 v2, v2, v3
	v_pk_add_f32 v[26:27], v[6:7], v[0:1] op_sel_hi:[1,0] neg_lo:[0,1] neg_hi:[0,1]
	v_add_f32_e32 v2, v4, v2
	v_pk_mul_f32 v[6:7], v[26:27], v[26:27]
	v_add_f32_e32 v2, v5, v2
	v_pk_add_f32 v[24:25], v[8:9], v[0:1] op_sel_hi:[1,0] neg_lo:[0,1] neg_hi:[0,1]
	v_add_f32_e32 v2, v6, v2
	v_pk_mul_f32 v[0:1], v[24:25], v[24:25]
	v_add_f32_e32 v2, v7, v2
	v_add_f32_e32 v0, v0, v2
	v_add_f32_e32 v0, v1, v0
	v_mov_b32_e32 v1, 0x3a27c5ac
	v_mov_b32_e32 v31, v145
	v_add_f32_dpp v0, v0, v0 quad_perm:[1,0,3,2] row_mask:0xf bank_mask:0xf bound_ctrl:1
	v_lshl_add_u64 v[30:31], v[50:51], 0, v[30:31]
	v_add_u32_e32 v40, s42, v40
	v_add_f32_dpp v0, v0, v0 quad_perm:[2,3,0,1] row_mask:0xf bank_mask:0xf bound_ctrl:1
	s_nop 1
	v_add_f32_dpp v0, v0, v0 row_half_mirror row_mask:0xf bank_mask:0xf bound_ctrl:1
	v_fmamk_f32 v0, v0, 0x3c800000, v1
	v_cmp_gt_f32_e32 vcc, s74, v0
	v_mul_f32_e32 v1, 0x4b800000, v0
	s_nop 0
	v_cndmask_b32_e32 v0, v0, v1, vcc
	v_rsq_f32_e32 v0, v0
	s_nop 0
	v_mul_f32_e32 v1, 0x45800000, v0
	v_cndmask_b32_e32 v42, v0, v1, vcc
	v_lshl_add_u64 v[0:1], v[10:11], 0, v[144:145]
	v_add_co_u32_e32 v0, vcc, s0, v0
	s_nop 1
	v_addc_co_u32_e32 v1, vcc, 0, v1, vcc
	s_waitcnt vmcnt(1)
	v_lshlrev_b32_e32 v37, 16, v216
	v_and_b32_e32 v35, 0xffff0000, v216
	v_lshlrev_b32_e32 v48, 16, v217
	v_and_b32_e32 v47, 0xffff0000, v217
	v_lshlrev_b32_e32 v46, 16, v218
	v_and_b32_e32 v45, 0xffff0000, v218
	v_lshlrev_b32_e32 v44, 16, v219
	v_and_b32_e32 v43, 0xffff0000, v219
	v_pk_mov_b32 v[50:51], v[28:29], v[200:201] op_sel:[1,0]
	v_mul_f32_e32 v221, v38, v42
	s_waitcnt vmcnt(0)
	v_pk_mul_f32 v[50:51], v[50:51], v[220:221]
	s_nop 0
	v_add_f32_e32 v8, v208, v51
	v_mul_f32_e32 v12, 0xbfb8aa3b, v37
	v_exp_f32_e32 v12, v12
	v_add_f32_e32 v8, v50, v8
	v_add_f32_e32 v12, 1.0, v12
	v_div_scale_f32 v29, s[0:1], v12, v12, v37
	v_rcp_f32_e32 v221, v29
	s_nop 0
	v_fma_f32 v38, -v29, v221, 1.0
	v_fmac_f32_e32 v221, v38, v221
	v_div_scale_f32 v38, vcc, v37, v12, v37
	v_mul_f32_e32 v49, v38, v221
	v_fma_f32 v50, -v29, v49, v38
	v_fmac_f32_e32 v49, v50, v221
	v_fma_f32 v29, -v29, v49, v38
	v_div_fmas_f32 v29, v29, v221, v49
	v_div_fixup_f32 v12, v29, v12, v37
	v_mul_f32_e32 v8, v12, v8
	v_mul_f32_e32 v12, 0xbfb8aa3b, v35
	v_exp_f32_e32 v12, v12
	v_mul_f32_e32 v37, v39, v42
	v_mov_b32_e32 v221, v201
	v_pk_mul_f32 v[36:37], v[220:221], v[36:37]
	v_add_f32_e32 v12, 1.0, v12
	v_add_f32_e32 v9, v209, v37
	v_div_scale_f32 v13, s[0:1], v12, v12, v35
	v_rcp_f32_e32 v29, v13
	v_add_f32_e32 v9, v36, v9
	v_fma_f32 v221, -v13, v29, 1.0
	v_fmac_f32_e32 v29, v221, v29
	v_div_scale_f32 v221, vcc, v35, v12, v35
	v_mul_f32_e32 v36, v221, v29
	v_fma_f32 v37, -v13, v36, v221
	v_fmac_f32_e32 v36, v37, v29
	v_fma_f32 v13, -v13, v36, v221
	v_div_fmas_f32 v13, v13, v29, v36
	v_div_fixup_f32 v12, v13, v12, v35
	v_mul_f32_e32 v35, v32, v42
	v_mov_b32_e32 v221, v202
	v_mul_f32_e32 v9, v12, v9
	v_pk_mul_f32 v[12:13], v[220:221], v[34:35]
	s_nop 0
	v_add_f32_e32 v10, v210, v13
	v_add_f32_e32 v10, v12, v10
	v_mul_f32_e32 v12, 0xbfb8aa3b, v48
	v_exp_f32_e32 v12, v12
	s_nop 0
	v_add_f32_e32 v12, 1.0, v12
	v_div_scale_f32 v13, s[0:1], v12, v12, v48
	v_rcp_f32_e32 v14, v13
	s_nop 0
	v_fma_f32 v29, -v13, v14, 1.0
	v_fmac_f32_e32 v14, v29, v14
	v_div_scale_f32 v29, vcc, v48, v12, v48
	v_mul_f32_e32 v221, v29, v14
	v_fma_f32 v32, -v13, v221, v29
	v_fmac_f32_e32 v221, v32, v14
	v_fma_f32 v13, -v13, v221, v29
	v_div_fmas_f32 v13, v13, v14, v221
	v_div_fixup_f32 v12, v13, v12, v48
	v_mul_f32_e32 v221, v33, v42
	v_mov_b32_e32 v29, v203
	v_mul_f32_e32 v12, v12, v10
	v_pk_mul_f32 v[10:11], v[28:29], v[220:221]
	v_mul_f32_e32 v221, v26, v42
	v_add_f32_e32 v11, v211, v11
	v_add_f32_e32 v10, v10, v11
	v_mul_f32_e32 v11, 0xbfb8aa3b, v47
	v_exp_f32_e32 v11, v11
	s_nop 0
	v_add_f32_e32 v11, 1.0, v11
	v_div_scale_f32 v13, s[0:1], v11, v11, v47
	v_rcp_f32_e32 v14, v13
	s_nop 0
	v_fma_f32 v15, -v13, v14, 1.0
	v_fmac_f32_e32 v14, v15, v14
	v_div_scale_f32 v15, vcc, v47, v11, v47
	v_mul_f32_e32 v28, v15, v14
	v_fma_f32 v29, -v13, v28, v15
	v_fmac_f32_e32 v28, v29, v14
	v_fma_f32 v13, -v13, v28, v15
	v_div_fmas_f32 v13, v13, v14, v28
	v_div_fixup_f32 v11, v13, v11, v47
	v_mul_f32_e32 v13, v11, v10
	v_pk_mov_b32 v[10:11], v[22:23], v[204:205] op_sel:[1,0]
	s_nop 0
	v_pk_mul_f32 v[10:11], v[10:11], v[220:221]
	v_mul_f32_e32 v221, v27, v42
	v_add_f32_e32 v0, v212, v11
	v_mul_f32_e32 v4, 0xbfb8aa3b, v46
	v_exp_f32_e32 v4, v4
	v_add_f32_e32 v0, v10, v0
	v_add_f32_e32 v4, 1.0, v4
	v_div_scale_f32 v10, s[0:1], v4, v4, v46
	v_rcp_f32_e32 v11, v10
	s_nop 0
	v_fma_f32 v14, -v10, v11, 1.0
	v_fmac_f32_e32 v11, v14, v11
	v_div_scale_f32 v14, vcc, v46, v4, v46
	v_mul_f32_e32 v15, v14, v11
	v_fma_f32 v23, -v10, v15, v14
	v_fmac_f32_e32 v15, v23, v11
	v_fma_f32 v10, -v10, v15, v14
	v_div_fmas_f32 v10, v10, v11, v15
	v_div_fixup_f32 v4, v10, v4, v46
	v_mov_b32_e32 v23, v205
	v_mul_f32_e32 v4, v4, v0
	v_pk_mul_f32 v[0:1], v[22:23], v[220:221]
	v_mul_f32_e32 v221, v24, v42
	v_add_f32_e32 v1, v213, v1
	v_add_f32_e32 v0, v0, v1
	v_mul_f32_e32 v1, 0xbfb8aa3b, v45
	v_exp_f32_e32 v1, v1
	s_nop 0
	v_add_f32_e32 v1, 1.0, v1
	v_div_scale_f32 v5, s[0:1], v1, v1, v45
	v_rcp_f32_e32 v10, v5
	s_nop 0
	v_fma_f32 v11, -v5, v10, 1.0
	v_fmac_f32_e32 v10, v11, v10
	v_div_scale_f32 v11, vcc, v45, v1, v45
	v_mul_f32_e32 v14, v11, v10
	v_fma_f32 v15, -v5, v14, v11
	v_fmac_f32_e32 v14, v15, v10
	v_fma_f32 v5, -v5, v14, v11
	v_div_fmas_f32 v5, v5, v10, v14
	v_div_fixup_f32 v1, v5, v1, v45
	v_mul_f32_e32 v5, v1, v0
	v_pk_mov_b32 v[0:1], v[20:21], v[206:207] op_sel:[1,0]
	v_mov_b32_e32 v21, v207
	v_pk_mul_f32 v[0:1], v[0:1], v[220:221]
	v_mul_f32_e32 v221, v25, v42
	v_add_f32_e32 v1, v214, v1
	v_add_f32_e32 v0, v0, v1
	v_mul_f32_e32 v1, 0xbfb8aa3b, v44
	v_exp_f32_e32 v1, v1
	s_nop 0
	v_add_f32_e32 v1, 1.0, v1
	v_div_scale_f32 v2, s[0:1], v1, v1, v44
	v_rcp_f32_e32 v6, v2
	s_nop 0
	v_fma_f32 v10, -v2, v6, 1.0
	v_fmac_f32_e32 v6, v10, v6
	v_div_scale_f32 v10, vcc, v44, v1, v44
	v_mul_f32_e32 v11, v10, v6
	v_fma_f32 v14, -v2, v11, v10
	v_fmac_f32_e32 v11, v14, v6
	v_fma_f32 v2, -v2, v11, v10
	v_div_fmas_f32 v2, v2, v6, v11
	v_div_fixup_f32 v1, v2, v1, v44
	v_mul_f32_e32 v6, v1, v0
	v_pk_mul_f32 v[0:1], v[20:21], v[220:221]
	s_nop 0
	v_add_f32_e32 v1, v215, v1
	v_add_f32_e32 v0, v0, v1
	v_mul_f32_e32 v1, 0xbfb8aa3b, v43
	v_exp_f32_e32 v1, v1
	s_nop 0
	v_add_f32_e32 v1, 1.0, v1
	v_div_scale_f32 v2, s[0:1], v1, v1, v43
	v_rcp_f32_e32 v3, v2
	s_mov_b32 s0, 0xfffff
	v_fma_f32 v7, -v2, v3, 1.0
	v_fmac_f32_e32 v3, v7, v3
	v_div_scale_f32 v7, vcc, v43, v1, v43
	v_mul_f32_e32 v10, v7, v3
	v_fma_f32 v11, -v2, v10, v7
	v_fmac_f32_e32 v10, v11, v3
	v_fma_f32 v2, -v2, v10, v7
	v_div_fmas_f32 v2, v2, v3, v10
	v_div_fixup_f32 v1, v2, v1, v43
	v_mul_f32_e32 v3, v1, v0
	v_cvt_pk_bf16_f32 v0, v8, v9
	v_cvt_pk_bf16_f32 v1, v12, v13
	v_cvt_pk_bf16_f32 v2, v4, v5
	v_lshlrev_b64 v[4:5], 10, v[18:19]
	v_lshl_add_u64 v[4:5], s[14:15], 0, v[4:5]
	v_cmp_lt_i32_e32 vcc, s0, v40
	v_lshl_add_u64 v[4:5], v[4:5], 0, v[144:145]
	s_or_b64 s[22:23], vcc, s[22:23]
	v_cvt_pk_bf16_f32 v3, v6, v3
	global_store_dwordx4 v[4:5], v[0:3], off
	s_andn2_b64 exec, exec, s[22:23]
	s_cbranch_execz .LBB0_901
.LBB0_897:
	v_ashrrev_i32_e32 v18, 6, v40
	v_lshrrev_b32_e32 v0, 3, v40
	v_ashrrev_i32_e32 v1, 15, v40
	v_and_b32_e32 v6, 0xfff, v18
	v_bfi_b32 v14, -8, v1, v0
	v_lshl_or_b32 v2, v14, 12, v6
	v_mov_b64_e32 v[0:1], s[10:11]
	v_mad_i64_i32 v[0:1], s[0:1], v2, s69, v[0:1]
	v_lshl_add_u64 v[0:1], v[0:1], 0, v[16:17]
	v_add_co_u32_e32 v0, vcc, 0x16bf0000, v0
	v_bfe_u32 v30, v40, 3, 3
	s_nop 0
	v_addc_co_u32_e32 v1, vcc, 0, v1, vcc
	global_load_dwordx4 v[196:199], v[0:1], off offset:768
	v_mov_b64_e32 v[4:5], s[12:13]
	v_lshl_or_b32 v31, v30, 6, v41
	v_mad_i64_i32 v[10:11], s[0:1], v18, s62, v[4:5]
	v_cmp_ne_u32_e32 vcc, 0, v6
	v_lshlrev_b32_e32 v12, 2, v31
	s_mov_b64 s[24:25], vcc
	v_mov_b32_e32 v13, v145
	v_lshl_add_u64 v[2:3], v[10:11], 0, v[12:13]
	v_lshl_add_u64 v[6:7], v[2:3], 0, s[88:89]
	v_add_co_u32_e32 v2, vcc, 0x1000, v2
	s_nop 1
	v_addc_co_u32_e32 v3, vcc, 0, v3, vcc
	global_load_dwordx4 v[2:5], v[2:3], off offset:2048
	global_load_dwordx4 v[6:9], v[6:7], off offset:16
	v_lshlrev_b32_e32 v144, 1, v31
	v_lshl_add_u64 v[222:223], v[10:11], 0, v[144:145]
	v_add_co_u32_e32 v222, vcc, 0x2000, v222
	s_nop 1
	v_addc_co_u32_e32 v223, vcc, 0, v223, vcc
	global_load_dwordx4 v[216:219], v[222:223], off offset:1280
	v_ashrrev_i32_e32 v19, 31, v18
	v_lshlrev_b64 v[224:225], 5, v[18:19]
	v_lshl_add_u64 v[224:225], s[16:17], 0, v[224:225]
	v_mov_b32_e32 v144, v30
	v_lshl_add_u64 v[224:225], v[144:145], 2, v[224:225]
	global_load_dword v220, v[224:225], off
	s_mov_b64 vcc, s[24:25]
	s_waitcnt vmcnt(4)
	v_and_b32_e32 v25, 0xffff0000, v197
	v_and_b32_e32 v24, 16, v196
	v_lshlrev_b32_e32 v26, 16, v196
	v_and_b32_e32 v22, 0xffff0000, v198
	v_lshlrev_b32_e32 v23, 16, v198
	v_and_b32_e32 v20, 0xffff0000, v199
	v_lshlrev_b32_e32 v21, 16, v199
	s_and_saveexec_b64 s[0:1], vcc
	s_xor_b64 s[24:25], exec, s[0:1]
	s_cbranch_execz .LBB0_899
	v_mov_b32_e32 v29, v26
	v_mov_b32_e32 v28, v25
.LBB0_899:
	s_or_saveexec_b64 s[24:25], s[24:25]
	v_and_b32_e32 v36, 0xffff0000, v196
	v_lshlrev_b32_e32 v34, 16, v197
	s_xor_b64 exec, exec, s[24:25]
	s_cbranch_execz .LBB0_896
	v_ashrrev_i32_e32 v15, 31, v14
	v_lshl_add_u64 v[0:1], v[14:15], 2, s[20:21]
	global_load_dword v0, v[0:1], off
	v_pk_mov_b32 v[28:29], v[24:25], v[26:27] op_sel:[1,0]
	s_waitcnt vmcnt(0)
	v_pk_mul_f32 v[8:9], v[0:1], v[22:23] op_sel_hi:[0,1]
	v_pk_mov_b32 v[2:3], v[28:29], v[28:29] op_sel:[1,0]
	v_pk_mov_b32 v[4:5], v[28:29], v[28:29] op_sel:[1,0]
	v_mov_b32_e32 v35, v3
	v_mov_b32_e32 v5, v36
	v_pk_mul_f32 v[2:3], v[0:1], v[4:5] op_sel_hi:[0,1]
	v_pk_mul_f32 v[4:5], v[0:1], v[34:35] op_sel_hi:[0,1]
	v_pk_mul_f32 v[0:1], v[0:1], v[20:21] op_sel_hi:[0,1]
	v_mov_b32_e32 v6, v9
	v_mov_b32_e32 v7, v8
	v_mov_b32_e32 v8, v1
	v_mov_b32_e32 v9, v0
	s_branch .LBB0_896
